# phase D: KV-up tiles / ctx-scan items reassigned so that no block gets latent-scan + KV tile + two ctx scans
# speedup vs baseline: 1.0114x; 1.0056x over previous
.LBB0_169:
	s_cmpk_lt_i32 s39, 0x200
	s_cbranch_scc1 .Ld_p512
	s_cmpk_lt_i32 s39, 0x250
	s_cbranch_scc1 .LBB0_182
	s_cmpk_lt_i32 s39, 0x400
	s_cbranch_scc1 .Ld_p512
	s_cmpk_lt_i32 s39, 0x500
	s_cbranch_scc1 .LBB0_182
	s_cmpk_lt_i32 s39, 0x550
	s_cbranch_scc1 .Ld_m256
	s_cmpk_lt_i32 s39, 0x5a0
	s_cbranch_scc1 .Ld_p176
	s_branch .LBB0_182
.Ld_m256:
	s_addk_i32 s39, 0xff00
	s_branch .LBB0_170
.Ld_p176:
	s_addk_i32 s39, 0xb0
	s_branch .LBB0_170
.Ld_p512:
	s_addk_i32 s39, 0x200
